# split grid barrier before the conv phase: wait taken after the conv loop's tap/bias loads are in flight
# baseline (speedup 1.0000x reference)
; __device__ __forceinline__ void xcd_barrier(const XcdBarrier& b) {
;     asm volatile("s_waitcnt vmcnt(0)" ::: "memory");
;     __syncthreads();
;     if (threadIdx.x == 0) {
;         unsigned* bar = b.bar;
;         __builtin_amdgcn_s_waitcnt(0);
;         unsigned nloc = b.st[0], nx = b.st[1];
;         if (nloc == 0u) { xcd_barrier_complete(bar, b.x, nloc, nx); b.st[0] = nloc; b.st[1] = nx; }
.LBB0_123:
	s_mov_b32 s98, 0
	s_cmp_gt_i32 s91, 2
	s_cselect_b64 s[2:3], -1, 0
	s_and_b64 s[0:1], s[0:1], s[2:3]
	s_andn2_b64 vcc, exec, s[0:1]
	s_cbranch_vccnz .LBB0_173
	s_cmp_eq_u32 s82, 0x100
	s_cselect_b32 s98, 1, 0
	s_waitcnt vmcnt(0)
	s_waitcnt vmcnt(0) lgkmcnt(0)
	s_barrier
	s_mov_b64 s[0:1], exec
	v_readlane_b32 s4, v254, 1
	v_readlane_b32 s5, v254, 2
	s_and_b64 s[4:5], s[0:1], s[4:5]
	s_mov_b64 exec, s[4:5]
	s_cbranch_execz .LBB0_172
	v_mov_b32_e32 v0, s52
	s_waitcnt vmcnt(0) expcnt(0) lgkmcnt(0)
	ds_read_b32 v2, v0
	ds_read_b32 v0, v0 offset:4
	s_waitcnt lgkmcnt(1)
	v_cmp_ne_u32_e32 vcc, 0, v2
	s_cbranch_vccnz .LBB0_140
	v_readlane_b32 s4, v254, 0
	s_mul_i32 s33, s83, s4
	s_add_u32 s4, s88, 0xffc0200
	s_addc_u32 s5, s89, 0
	s_add_u32 s6, s88, 0xffc0400
	s_addc_u32 s7, s89, 0
	s_add_u32 s8, s88, 0xffc0500
	s_addc_u32 s9, s89, 0
	s_add_u32 s10, s88, 0xffc0600
	s_addc_u32 s11, s89, 0
	s_add_u32 s12, s88, 0xffc0700
	s_addc_u32 s13, s89, 0
	s_add_u32 s14, s88, 0xffc0800
	s_addc_u32 s15, s89, 0
	s_add_u32 s16, s88, 0xffc0900
	s_addc_u32 s17, s89, 0
	s_add_u32 s18, s88, 0xffc0a00
	s_addc_u32 s19, s89, 0
	s_add_u32 s20, s88, 0xffc0b00
	s_addc_u32 s21, s89, 0
	s_add_u32 s22, s88, 0xffc0c00
	s_addc_u32 s23, s89, 0
	s_add_u32 s24, s88, 0xffc0d00
	s_addc_u32 s25, s89, 0
	s_add_u32 s26, s88, 0xffc0e00
	s_addc_u32 s27, s89, 0
	s_add_u32 s28, s88, 0xffc0f00
	s_addc_u32 s29, s89, 0
	s_add_u32 s30, s88, 0xffc1000
	s_addc_u32 s31, s89, 0
	s_add_u32 s34, s88, 0xffc1100
	s_addc_u32 s35, s89, 0
	s_add_u32 s36, s88, 0xffc1200
	s_addc_u32 s37, s89, 0
	s_add_u32 s38, s88, 0xffc1300
	s_mul_i32 s33, s33, s82
	s_addc_u32 s39, s89, 0
	s_mov_b32 s46, 1
	v_mov_b32_e32 v16, 0
	s_branch .LBB0_128

; __device__ __forceinline__ unsigned xb_ld(unsigned* p)              { return __hip_atomic_load(p, __ATOMIC_RELAXED, __HIP_MEMORY_SCOPE_AGENT); }
; __device__ __forceinline__ unsigned xb_add(unsigned* p, unsigned v) { return __hip_atomic_fetch_add(p, v, __ATOMIC_RELAXED, __HIP_MEMORY_SCOPE_AGENT); }
; #define XB_SPIN(cond, bar) do { unsigned _sp = 0; while (cond) { __builtin_amdgcn_s_sleep(1); \
;     if ((++_sp & 255u) == 0u) { if (xb_ld(&(bar)[XB_TMO])) break; if (_sp > XB_SPIN_CAP) { atomicAdd(&(bar)[XB_TMO], 1u); break; } } } } while (0)
; __device__ __forceinline__ void xcd_barrier_complete(unsigned* bar, unsigned x, unsigned& nloc, unsigned& nx) {
;     ...
;         for (unsigned j = 0; j < 16; ++j) { const unsigned c = xb_ld(&bar[XB_XCNT(j)]); sum += c; cnt += (c > 0u) ? 1u : 0u; mine = (j == x) ? c : mine; }
;         if (sum == G) break;
;         __builtin_amdgcn_s_sleep(1);
;         if ((++sp & 255u) == 0u) { if (xb_ld(&bar[XB_TMO])) break; if (sp > XB_SPIN_CAP) { atomicAdd(&bar[XB_TMO], 1u); break; } }
;     }
;     nloc = mine > 0u ? mine : 1u; nx = cnt > 0u ? cnt : 1u;
; }
; __device__ __forceinline__ void xcd_barrier(const XcdBarrier& b) {
;     asm volatile("s_waitcnt vmcnt(0)" ::: "memory");
;     __syncthreads();
;     if (threadIdx.x == 0) {
;         unsigned* bar = b.bar;
;         __builtin_amdgcn_s_waitcnt(0);
;         unsigned nloc = b.st[0], nx = b.st[1];
;         if (nloc == 0u) { xcd_barrier_complete(bar, b.x, nloc, nx); b.st[0] = nloc; b.st[1] = nx; }
;         const unsigned old = xb_add(&bar[XB_XSUB(b.x)], 1u);
;         const unsigned gen = old / nloc;
;         if (old + 1u == (gen + 1u) * nloc) {
;             __builtin_amdgcn_fence(__ATOMIC_RELEASE, "agent");
;             asm volatile("s_waitcnt vmcnt(0)" ::: "memory");
;             const unsigned og = xb_add(&bar[XB_TOP], 1u);
;             const unsigned tg = og / nx;
;             if (og + 1u == (tg + 1u) * nx) xb_add(&bar[XB_TOPGEN], 1u);
;             else XB_SPIN(xb_ld(&bar[XB_TOPGEN]) == tg, bar);
;             __builtin_amdgcn_fence(__ATOMIC_ACQUIRE, "agent");
;             xb_add(&bar[XB_XGEN(b.x)], 1u);
;             asm volatile("s_waitcnt vmcnt(0)" ::: "memory");
;         } else {
;             XB_SPIN(xb_ld(&bar[XB_XGEN(b.x)]) == gen, bar);
.LBB0_139:
	v_readlane_b32 s4, v254, 3
	s_cmp_eq_u32 s4, 0
	s_cselect_b64 vcc, -1, 0
	s_cmp_eq_u32 s4, 1
	v_cndmask_b32_e32 v16, 0, v15, vcc
	s_cselect_b64 vcc, -1, 0
	s_cmp_eq_u32 s4, 2
	v_cndmask_b32_e32 v16, v16, v0, vcc
	s_cselect_b64 vcc, -1, 0
	s_cmp_eq_u32 s4, 3
	v_cndmask_b32_e32 v16, v16, v1, vcc
	s_cselect_b64 vcc, -1, 0
	s_cmp_eq_u32 s4, 4
	v_cndmask_b32_e32 v16, v16, v2, vcc
	s_cselect_b64 vcc, -1, 0
	s_cmp_eq_u32 s4, 5
	v_cndmask_b32_e32 v16, v16, v3, vcc
	s_cselect_b64 vcc, -1, 0
	s_cmp_eq_u32 s4, 6
	v_cndmask_b32_e32 v16, v16, v4, vcc
	s_cselect_b64 vcc, -1, 0
	s_cmp_eq_u32 s4, 7
	v_cndmask_b32_e32 v16, v16, v5, vcc
	s_cselect_b64 vcc, -1, 0
	s_cmp_eq_u32 s4, 8
	v_cndmask_b32_e32 v16, v16, v6, vcc
	s_cselect_b64 vcc, -1, 0
	s_cmp_eq_u32 s4, 9
	v_cndmask_b32_e32 v16, v16, v7, vcc
	s_cselect_b64 vcc, -1, 0
	s_cmp_eq_u32 s4, 10
	v_cndmask_b32_e32 v16, v16, v8, vcc
	s_cselect_b64 vcc, -1, 0
	s_cmp_eq_u32 s4, 11
	v_cndmask_b32_e32 v16, v16, v9, vcc
	s_cselect_b64 vcc, -1, 0
	s_cmp_eq_u32 s4, 12
	v_cndmask_b32_e32 v16, v16, v10, vcc
	s_cselect_b64 vcc, -1, 0
	s_cmp_eq_u32 s4, 13
	v_cndmask_b32_e32 v16, v16, v11, vcc
	s_cselect_b64 vcc, -1, 0
	s_cmp_eq_u32 s4, 14
	v_cndmask_b32_e32 v16, v16, v12, vcc
	s_cselect_b64 vcc, -1, 0
	s_cmp_eq_u32 s4, 15
	v_cndmask_b32_e32 v16, v16, v13, vcc
	s_cselect_b64 vcc, -1, 0
	v_cndmask_b32_e32 v16, v16, v14, vcc
	v_cmp_ne_u32_e32 vcc, 0, v15
	s_nop 1
	v_cndmask_b32_e64 v15, 0, 1, vcc
	v_cmp_ne_u32_e32 vcc, 0, v0
	s_nop 1
	v_addc_co_u32_e32 v0, vcc, 0, v15, vcc
	v_cmp_ne_u32_e32 vcc, 0, v1
	s_nop 1
	v_cndmask_b32_e64 v1, 0, 1, vcc
	v_cmp_ne_u32_e32 vcc, 0, v2
	v_max_u32_e32 v2, 1, v16
	s_nop 0
	v_addc_co_u32_e32 v0, vcc, v0, v1, vcc
	v_cmp_ne_u32_e32 vcc, 0, v3
	s_nop 1
	v_cndmask_b32_e64 v1, 0, 1, vcc
	v_cmp_ne_u32_e32 vcc, 0, v4
	s_nop 1
	v_addc_co_u32_e32 v0, vcc, v0, v1, vcc
	v_cmp_ne_u32_e32 vcc, 0, v5
	s_nop 1
	v_cndmask_b32_e64 v1, 0, 1, vcc
	v_cmp_ne_u32_e32 vcc, 0, v6
	s_nop 1
	v_addc_co_u32_e32 v0, vcc, v0, v1, vcc
	v_cmp_ne_u32_e32 vcc, 0, v7
	s_nop 1
	v_cndmask_b32_e64 v1, 0, 1, vcc
	v_cmp_ne_u32_e32 vcc, 0, v8
	s_nop 1
	v_addc_co_u32_e32 v0, vcc, v0, v1, vcc
	v_cmp_ne_u32_e32 vcc, 0, v9
	s_nop 1
	v_cndmask_b32_e64 v1, 0, 1, vcc
	v_cmp_ne_u32_e32 vcc, 0, v10
	s_nop 1
	v_addc_co_u32_e32 v0, vcc, v0, v1, vcc
	v_cmp_ne_u32_e32 vcc, 0, v11
	s_nop 1
	v_cndmask_b32_e64 v1, 0, 1, vcc
	v_cmp_ne_u32_e32 vcc, 0, v12
	s_nop 1
	v_addc_co_u32_e32 v0, vcc, v0, v1, vcc
	v_cmp_ne_u32_e32 vcc, 0, v13
	s_nop 1
	v_cndmask_b32_e64 v1, 0, 1, vcc
	v_cmp_ne_u32_e32 vcc, 0, v14
	s_nop 1
	v_addc_co_u32_e32 v0, vcc, v0, v1, vcc
	v_max_u32_e32 v0, 1, v0
	v_mov_b32_e32 v1, s52
	ds_write_b32 v1, v2
	ds_write_b32 v1, v0 offset:4
.LBB0_140:
	v_readlane_b32 s4, v254, 3
	s_lshl_b32 s4, s4, 8
	s_add_u32 s4, s92, s4
	s_addc_u32 s5, s93, 0
	v_mov_b32_e32 v1, 0x1000
	v_mov_b32_e32 v3, 1
	global_atomic_add v3, v1, v3, s[4:5] offset:1024 sc0
	v_cvt_f32_u32_e32 v1, v2
	v_sub_u32_e32 v4, 0, v2
	v_rcp_iflag_f32_e32 v1, v1
	s_nop 0
	v_mul_f32_e32 v1, 0x4f7ffffe, v1
	v_cvt_u32_f32_e32 v1, v1
	v_mul_lo_u32 v4, v4, v1
	v_mul_hi_u32 v4, v1, v4
	v_add_u32_e32 v1, v1, v4
	s_waitcnt vmcnt(0)
	v_mul_hi_u32 v1, v3, v1
	v_mul_lo_u32 v4, v1, v2
	v_sub_u32_e32 v4, v3, v4
	v_add_u32_e32 v5, 1, v1
	v_cmp_ge_u32_e32 vcc, v4, v2
	v_add_u32_e32 v3, 1, v3
	s_nop 0
	v_cndmask_b32_e32 v1, v1, v5, vcc
	v_sub_u32_e32 v5, v4, v2
	v_cndmask_b32_e32 v4, v4, v5, vcc
	v_add_u32_e32 v5, 1, v1
	v_cmp_ge_u32_e32 vcc, v4, v2
	s_nop 1
	v_cndmask_b32_e32 v1, v1, v5, vcc
	v_mul_lo_u32 v4, v2, v1
	v_add_u32_e32 v2, v4, v2
	v_cmp_ne_u32_e32 vcc, v3, v2
	s_and_saveexec_b64 s[6:7], vcc
	s_xor_b64 s[6:7], exec, s[6:7]
	s_cbranch_execz .LBB0_154
	s_cmp_eq_u32 s98, 1
	s_cbranch_scc1 .Lsk1_nl
	s_waitcnt lgkmcnt(0)
	v_mov_b32_e32 v0, 0x2000
	global_load_dword v0, v0, s[4:5] offset:1024 sc1
	s_add_u32 s12, s4, 0x2400
	s_addc_u32 s13, s5, 0
	s_waitcnt vmcnt(0)
	v_cmp_eq_u32_e32 vcc, v0, v1
	s_and_saveexec_b64 s[8:9], vcc
	s_cbranch_execz .LBB0_153
	s_add_u32 s10, s88, 0xffc0200
	s_addc_u32 s11, s89, 0
	s_mov_b32 s24, 1
	s_mov_b64 s[14:15], 0
	v_mov_b32_e32 v0, 0
	s_branch .LBB0_144

; __device__ __forceinline__ unsigned xb_ld(unsigned* p)              { return __hip_atomic_load(p, __ATOMIC_RELAXED, __HIP_MEMORY_SCOPE_AGENT); }
; __device__ __forceinline__ unsigned xb_add(unsigned* p, unsigned v) { return __hip_atomic_fetch_add(p, v, __ATOMIC_RELAXED, __HIP_MEMORY_SCOPE_AGENT); }
; #define XB_SPIN(cond, bar) do { unsigned _sp = 0; while (cond) { __builtin_amdgcn_s_sleep(1); \
;     if ((++_sp & 255u) == 0u) { if (xb_ld(&(bar)[XB_TMO])) break; if (_sp > XB_SPIN_CAP) { atomicAdd(&(bar)[XB_TMO], 1u); break; } } } } while (0)
; __device__ __forceinline__ void xcd_barrier(const XcdBarrier& b) {
;     ...
;             else XB_SPIN(xb_ld(&bar[XB_TOPGEN]) == tg, bar);
;             __builtin_amdgcn_fence(__ATOMIC_ACQUIRE, "agent");
;             xb_add(&bar[XB_XGEN(b.x)], 1u);
;             asm volatile("s_waitcnt vmcnt(0)" ::: "memory");
;         } else {
;             XB_SPIN(xb_ld(&bar[XB_XGEN(b.x)]) == gen, bar);
; __device__ __forceinline__ void p_conv(const Params& p) {
;     ...
;         float cw[4][8], cb[8];
; #pragma unroll
;         for (int w = 0; w < 4; ++w) { const float4 a = *(const float4*)(p.conv_w + w * 2048 + ch), b = *(const float4*)(p.conv_w + w * 2048 + ch + 4);
;             cw[w][0] = a.x; cw[w][1] = a.y; cw[w][2] = a.z; cw[w][3] = a.w; cw[w][4] = b.x; cw[w][5] = b.y; cw[w][6] = b.z; cw[w][7] = b.w; }
;         { const float4 a = *(const float4*)(p.conv_b + ch), b = *(const float4*)(p.conv_b + ch + 4);
;             cb[0] = a.x; cb[1] = a.y; cb[2] = a.z; cb[3] = a.w; cb[4] = b.x; cb[5] = b.y; cb[6] = b.z; cb[7] = b.w; }
.LBB0_177:
	s_and_b32 s14, s13, 7
	v_readlane_b32 s16, v254, 4
	v_lshl_or_b32 v48, s14, 8, v103
	v_readlane_b32 s17, v254, 5
	v_readlane_b32 s18, v254, 6
	v_readlane_b32 s19, v254, 7
	v_readlane_b32 s20, v254, 8
	v_readlane_b32 s21, v254, 9
	v_readlane_b32 s24, v254, 12
	v_readlane_b32 s25, v254, 13
	v_lshlrev_b32_e32 v72, 2, v48
	v_readlane_b32 s26, v254, 14
	v_readlane_b32 s27, v254, 15
	v_readlane_b32 s28, v254, 16
	v_readlane_b32 s29, v254, 17
	s_mov_b64 s[16:17], s[24:25]
	v_lshl_add_u64 v[8:9], s[16:17], 0, v[72:73]
	v_add_co_u32_e32 v42, vcc, 0x2000, v8
	v_lshl_add_u64 v[10:11], v[8:9], 0, s[2:3]
	s_nop 0
	v_addc_co_u32_e32 v43, vcc, 0, v9, vcc
	v_add_co_u32_e32 v44, vcc, 0x4000, v8
	v_lshl_add_u64 v[12:13], v[8:9], 0, s[4:5]
	s_nop 0
	v_addc_co_u32_e32 v45, vcc, 0, v9, vcc
	v_add_co_u32_e32 v46, vcc, 0x6000, v8
	s_mov_b64 s[18:19], s[26:27]
	v_lshl_add_u64 v[40:41], v[8:9], 0, s[6:7]
	global_load_dwordx4 v[0:3], v[10:11], off offset:16
	global_load_dwordx4 v[4:7], v[12:13], off offset:16
	v_addc_co_u32_e32 v47, vcc, 0, v9, vcc
	global_load_dwordx4 v[24:27], v[44:45], off
	global_load_dwordx4 v[20:23], v[46:47], off
	global_load_dwordx4 v[28:31], v[42:43], off
	global_load_dwordx4 v[8:11], v[40:41], off offset:16
	global_load_dwordx4 v[12:15], v72, s[16:17] offset:16
	global_load_dwordx4 v[16:19], v72, s[18:19] offset:16
	global_load_dwordx4 v[32:35], v72, s[16:17]
	global_load_dwordx4 v[36:39], v72, s[18:19]
	s_cmp_eq_u32 s98, 1
	s_cbranch_scc0 .Lw1_done
	s_mov_b32 s98, 0
	v_readfirstlane_b32 s96, v212
	s_nop 3
	s_cmp_lg_u32 s96, 0
	s_cbranch_scc1 .Lw1_bar
	v_readlane_b32 s96, v254, 3
	s_nop 3
	s_lshl_b32 s96, s96, 8
	v_mov_b32_e32 v250, 0xffc3500
	v_mov_b32_e32 v251, 0xffc2400
	v_add_u32_e32 v251, s96, v251
	s_mov_b32 s96, 0
.Lw1_spin:
	global_load_dword v252, v250, s[88:89] sc1
	global_load_dword v253, v251, s[88:89] sc1
	s_waitcnt vmcnt(0)
	v_min_u32_e32 v252, v252, v253
	s_nop 1
	v_readfirstlane_b32 s97, v252
	s_nop 3
	s_cmp_ge_u32 s97, 2
	s_cbranch_scc1 .Lw1_acq
	s_sleep 1
	s_add_i32 s96, s96, 1
	s_cmp_lt_u32 s96, 0x40000
	s_cbranch_scc1 .Lw1_spin

; __device__ __forceinline__ void p_conv(const Params& p) {
;     ...
;         u32x4 raw[11];
; #pragma unroll
;         for (int i = 0; i < 11; ++i) {
;             const int rr = s0 - 3 + i;
;             if (seq0 + rr >= 0) raw[i] = __builtin_nontemporal_load((const u32x4*)(R1 + (size_t)(tok0 + rr) * 5120 + ch)); else raw[i] = (u32x4){0u, 0u, 0u, 0u};
.Lw1_done:
	v_readlane_b32 s8, v254, 20
	s_orn2_b32 s16, 0xfffff87f, s10
	v_lshlrev_b32_e32 v72, 1, v48
	v_readlane_b32 s9, v254, 21
	s_and_b32 s15, s10, 0xffffff80
	v_cmp_lt_i32_e32 vcc, s16, v104
	v_lshl_add_u64 v[40:41], s[8:9], 0, v[72:73]
	v_mov_b32_e32 v58, 0
	v_mov_b32_e32 v59, 0
	v_mov_b32_e32 v60, 0
	v_mov_b32_e32 v61, 0
	v_readlane_b32 s22, v254, 10
	v_readlane_b32 s23, v254, 11
	v_readlane_b32 s30, v254, 18
	v_readlane_b32 s31, v254, 19
	s_mov_b64 s[20:21], s[28:29]
	s_and_saveexec_b64 s[8:9], vcc
	s_cbranch_execz .LBB0_179
	v_add_u32_e32 v42, s15, v104
	v_mad_i64_i32 v[42:43], s[18:19], v42, s12, v[40:41]
	global_load_dwordx4 v[58:61], v[42:43], off nt
